# plus: removed four dead VALU ops per iteration from the NOMAX diff loop (stale DMA address temps, +0.0 adds)
# speedup vs baseline: 1.0021x; 1.0021x over previous
; #define TWAIT_BAR(N) asm volatile("s_waitcnt vmcnt(" #N ") lgkmcnt(0)\n\ts_barrier" ::: "memory")
; #define RESC() do { if constexpr (!NOMAX) if (resc) { asm volatile("s_waitcnt lgkmcnt(0)" ::: "memory"); \
;         _Pragma("unroll") for (int d_ = 0; d_ < 2; ++d_) _Pragma("unroll") for (int r = 0; r < 16; ++r) o[d_][r] *= wsf[crow(r, hi)]; } } while (0)
; #define ROT() do { sl_prev = sl_cur; sl_cur = sl_next; sl_next = (sl_next == 2 * SLOTB) ? 0 : sl_next + SLOTB; } while (0)
; #define RESC() do { if constexpr (!NOMAX) if (resc) { asm volatile("s_waitcnt lgkmcnt(0)" ::: "memory"); \
;         _Pragma("unroll") for (int d_ = 0; d_ < 4; ++d_) _Pragma("unroll") for (int r = 0; r < 16; ++r) o[d_][r] *= wsf[crow(r, hi)]; } } while (0)
; #define ROT() do { sl_prev = sl_cur; sl_cur = sl_next; sl_next = (sl_next == 2) ? 0 : sl_next + 1; } while (0)
; #define RESC() do { if (resc) { asm volatile("s_waitcnt lgkmcnt(0)" ::: "memory"); \
;         _Pragma("unroll") for (int d_ = 0; d_ < 4; ++d_) _Pragma("unroll") for (int r = 0; r < 16; ++r) o[d_][r] *= wsf[crow(r, hi)]; } } while (0)
; template <bool NOMAX>
; __device__ __forceinline__ void diff_unit(const AttnCtx& C, int u, LAS unsigned char* lds) {
;     ...
;     int kk = 1;
;     for (; kk + 7 < n; kk += 2) {
;         STEP(pB0, pB1, pA0, pA1, kk, true, true, true, false);     TWAIT_BAR(3); RESC(); ROT();
;         STEP(pA0, pA1, pB0, pB1, kk + 1, true, true, true, false); TWAIT_BAR(3); RESC(); ROT();
.LBB0_463:
	s_mov_b32 s8, s60
	s_mov_b32 s9, s16
	s_mov_b32 s10, s59
	ds_read_b128 v[4:7], v219 offset:1024
	v_lshl_add_u32 v207, s11, 14, v214
	v_add_f32_e32 v2, v100, v101
	v_add_f32_e32 v2, v102, v2
	v_add_f32_e32 v2, v103, v2
	v_add_f32_e32 v2, v104, v2
	v_add_f32_e32 v2, v105, v2
	v_cvt_pk_bf16_f32 v160, v100, v101
	v_cvt_pk_bf16_f32 v161, v102, v103
	s_waitcnt lgkmcnt(1)
	v_mfma_f32_32x32x16_bf16 v[132:147], v[192:195], v[116:119], 0
	v_mfma_f32_32x32x16_bf16 v[116:131], v[184:187], v[116:119], 0
	v_add_f32_e32 v2, v106, v2
	v_add_f32_e32 v2, v107, v2
	v_add_f32_e32 v2, v108, v2
	v_add_f32_e32 v2, v109, v2
	v_cvt_pk_bf16_f32 v162, v104, v105
	v_cvt_pk_bf16_f32 v163, v106, v107
	ds_read_b128 v[10:13], v219 offset:2048
	ds_read_b64_tr_b16 v[14:15], v207 offset:24576
	ds_read_b64_tr_b16 v[16:17], v207 offset:25088
	v_add_f32_e32 v2, v110, v2
	v_add_f32_e32 v2, v111, v2
	v_add_f32_e32 v2, v112, v2
	v_add_f32_e32 v2, v113, v2
	v_cvt_pk_bf16_f32 v156, v108, v109
	v_cvt_pk_bf16_f32 v157, v110, v111
	s_waitcnt lgkmcnt(3)
	v_mfma_f32_32x32x16_bf16 v[132:147], v[188:191], v[4:7], v[132:147]
	v_mfma_f32_32x32x16_bf16 v[116:131], v[180:183], v[4:7], v[116:131]
	v_add_f32_e32 v2, v114, v2
	v_add_f32_e32 v2, v115, v2
	v_add_f32_e32 v2, v84, v2
	v_add_f32_e32 v2, v85, v2
	v_cvt_pk_bf16_f32 v158, v112, v113
	v_cvt_pk_bf16_f32 v159, v114, v115
	ds_read_b128 v[4:7], v219 offset:3072
	ds_read_b64_tr_b16 v[100:101], v207 offset:28672
	ds_read_b64_tr_b16 v[102:103], v207 offset:29184
	v_add_f32_e32 v2, v86, v2
	v_add_f32_e32 v2, v87, v2
	v_add_f32_e32 v2, v88, v2
	v_add_f32_e32 v2, v89, v2
	v_cvt_pk_bf16_f32 v152, v84, v85
	v_cvt_pk_bf16_f32 v153, v86, v87
	s_waitcnt lgkmcnt(5)
	v_mfma_f32_32x32x16_bf16 v[132:147], v[176:179], v[10:13], v[132:147]
	v_mfma_f32_32x32x16_bf16 v[116:131], v[172:175], v[10:13], v[116:131]
	v_add_f32_e32 v2, v90, v2
	v_add_f32_e32 v2, v91, v2
	v_add_f32_e32 v2, v92, v2
	v_add_f32_e32 v2, v93, v2
	v_cvt_pk_bf16_f32 v154, v88, v89
	v_cvt_pk_bf16_f32 v155, v90, v91
	ds_read_b64_tr_b16 v[84:85], v207 offset:25600
	ds_read_b64_tr_b16 v[86:87], v207 offset:26112
	v_add_f32_e32 v2, v94, v2
	v_add_f32_e32 v2, v95, v2
	v_add_f32_e32 v2, v96, v2
	v_add_f32_e32 v2, v97, v2
	v_cvt_pk_bf16_f32 v148, v92, v93
	v_cvt_pk_bf16_f32 v149, v94, v95
	s_waitcnt lgkmcnt(4)
	v_mfma_f32_32x32x16_bf16 v[132:147], v[168:171], v[4:7], v[132:147]
	v_mfma_f32_32x32x16_bf16 v[116:131], v[164:167], v[4:7], v[116:131]
	v_add_f32_e32 v2, v98, v2
	v_add_f32_e32 v2, v99, v2
	v_cvt_pk_bf16_f32 v150, v96, v97
	v_cvt_pk_bf16_f32 v151, v98, v99
	v_add_f32_e32 v2, v225, v2
	ds_read_b64_tr_b16 v[4:5], v207 offset:29696
	ds_read_b64_tr_b16 v[6:7], v207 offset:30208
	v_mfma_f32_32x32x16_bf16 v[68:83], v[160:163], v[14:17], v[68:83]
	v_exp_f32_e32 v132, v132
	v_exp_f32_e32 v133, v133
	ds_read_b64_tr_b16 v[14:15], v207 offset:26624
	ds_read_b64_tr_b16 v[16:17], v207 offset:27136
	s_waitcnt lgkmcnt(6)
	v_mfma_f32_32x32x16_bf16 v[52:67], v[160:163], v[100:103], v[52:67]
	v_exp_f32_e32 v134, v134
	v_exp_f32_e32 v135, v135
	s_add_u32 s98, s6, s28
	s_addc_u32 s99, s7, s29
	v_lshl_add_u64 v[254:255], v[204:205], 0, s[98:99]
	s_lshl_b32 s100, s59, 13
	s_add_i32 s100, s100, s49
	s_mov_b32 m0, s100
	s_nop 0
	global_load_lds_dwordx4 v[254:255], off
	ds_read_b64_tr_b16 v[88:89], v207 offset:30720
	ds_read_b64_tr_b16 v[90:91], v207 offset:31232
	s_waitcnt lgkmcnt(6)
	v_mfma_f32_32x32x16_bf16 v[68:83], v[156:159], v[84:87], v[68:83]
	v_exp_f32_e32 v136, v136
	v_exp_f32_e32 v137, v137
	ds_read_b64_tr_b16 v[84:85], v207 offset:27648
	ds_read_b64_tr_b16 v[86:87], v207 offset:28160
	s_waitcnt lgkmcnt(6)
	v_mfma_f32_32x32x16_bf16 v[52:67], v[156:159], v[4:7], v[52:67]
	v_exp_f32_e32 v138, v138
	v_exp_f32_e32 v139, v139
	ds_read_b64_tr_b16 v[4:5], v207 offset:31744
	ds_read_b64_tr_b16 v[6:7], v207 offset:32256
	s_waitcnt lgkmcnt(6)
	v_mfma_f32_32x32x16_bf16 v[68:83], v[152:155], v[14:17], v[68:83]
	v_exp_f32_e32 v140, v140
	v_exp_f32_e32 v141, v141
	s_add_u32 s98, s6, s30
	s_addc_u32 s99, s7, s31
	v_lshl_add_u64 v[254:255], v[8:9], 0, s[98:99]
	s_lshl_b32 s100, s60, 14
	s_add_i32 s100, s100, s58
	s_mov_b32 m0, s100
	s_nop 0
	global_load_lds_dwordx4 v[254:255], off
	ds_read_b64_tr_b16 v[14:15], v207 offset:32768
	ds_read_b64_tr_b16 v[16:17], v207 offset:33280
	s_waitcnt lgkmcnt(6)
	v_mfma_f32_32x32x16_bf16 v[52:67], v[152:155], v[88:91], v[52:67]
	v_exp_f32_e32 v142, v142
	v_exp_f32_e32 v143, v143
	ds_read_b64_tr_b16 v[88:89], v207 offset:36864
	ds_read_b64_tr_b16 v[90:91], v207 offset:37376
	s_waitcnt lgkmcnt(6)
	v_mfma_f32_32x32x16_bf16 v[68:83], v[148:151], v[84:87], v[68:83]
	v_exp_f32_e32 v144, v144
	v_exp_f32_e32 v145, v145
	ds_read_b64_tr_b16 v[84:85], v207 offset:33792
	ds_read_b64_tr_b16 v[86:87], v207 offset:34304
	s_waitcnt lgkmcnt(6)
	v_mfma_f32_32x32x16_bf16 v[52:67], v[148:151], v[4:7], v[52:67]
	v_exp_f32_e32 v146, v146
	v_exp_f32_e32 v147, v147
	ds_read_b64_tr_b16 v[92:93], v207 offset:37888
	ds_read_b64_tr_b16 v[94:95], v207 offset:38400
	s_lshl_b32 s11, s60, 13
	v_add_u32_e32 v4, s11, v222
	ds_read_b128 v[96:99], v4
	ds_read_b128 v[164:167], v4 offset:512
	s_waitcnt lgkmcnt(8)
	v_mfma_f32_32x32x16_bf16 v[36:51], v[160:163], v[14:17], v[36:51]
	v_exp_f32_e32 v116, v116
	v_exp_f32_e32 v117, v117
	ds_read_b64_tr_b16 v[14:15], v207 offset:34816
	ds_read_b64_tr_b16 v[16:17], v207 offset:35328
	ds_read_b128 v[168:171], v4 offset:2048
	ds_read_b128 v[172:175], v4 offset:2560
	s_waitcnt lgkmcnt(10)
	v_mfma_f32_32x32x16_bf16 v[20:35], v[160:163], v[88:91], v[20:35]
	v_exp_f32_e32 v118, v118
	v_exp_f32_e32 v119, v119
	ds_read_b64_tr_b16 v[88:89], v207 offset:38912
	ds_read_b64_tr_b16 v[90:91], v207 offset:39424
	ds_read_b128 v[176:179], v4 offset:4096
	ds_read_b128 v[180:183], v4 offset:4608
	s_waitcnt lgkmcnt(12)
; #define TWAIT_BAR(N) asm volatile("s_waitcnt vmcnt(" #N ") lgkmcnt(0)\n\ts_barrier" ::: "memory")
; #define RESC() do { if constexpr (!NOMAX) if (resc) { asm volatile("s_waitcnt lgkmcnt(0)" ::: "memory"); \
;         _Pragma("unroll") for (int d_ = 0; d_ < 2; ++d_) _Pragma("unroll") for (int r = 0; r < 16; ++r) o[d_][r] *= wsf[crow(r, hi)]; } } while (0)
; #define ROT() do { sl_prev = sl_cur; sl_cur = sl_next; sl_next = (sl_next == 2 * SLOTB) ? 0 : sl_next + SLOTB; } while (0)
; #define RESC() do { if constexpr (!NOMAX) if (resc) { asm volatile("s_waitcnt lgkmcnt(0)" ::: "memory"); \
;         _Pragma("unroll") for (int d_ = 0; d_ < 4; ++d_) _Pragma("unroll") for (int r = 0; r < 16; ++r) o[d_][r] *= wsf[crow(r, hi)]; } } while (0)
; #define ROT() do { sl_prev = sl_cur; sl_cur = sl_next; sl_next = (sl_next == 2) ? 0 : sl_next + 1; } while (0)
; #define RESC() do { if (resc) { asm volatile("s_waitcnt lgkmcnt(0)" ::: "memory"); \
;         _Pragma("unroll") for (int d_ = 0; d_ < 4; ++d_) _Pragma("unroll") for (int r = 0; r < 16; ++r) o[d_][r] *= wsf[crow(r, hi)]; } } while (0)
; template <bool NOMAX>
; __device__ __forceinline__ void diff_unit(const AttnCtx& C, int u, LAS unsigned char* lds) {
;     ...
;     int kk = 1;
;     for (; kk + 7 < n; kk += 2) {
;         STEP(pB0, pB1, pA0, pA1, kk, true, true, true, false);     TWAIT_BAR(3); RESC(); ROT();
;         STEP(pA0, pA1, pB0, pB1, kk + 1, true, true, true, false); TWAIT_BAR(3); RESC(); ROT();
	v_mfma_f32_32x32x16_bf16 v[36:51], v[156:159], v[84:87], v[36:51]
	v_exp_f32_e32 v120, v120
	v_exp_f32_e32 v121, v121
	ds_read_b64_tr_b16 v[84:85], v207 offset:35840
	ds_read_b64_tr_b16 v[86:87], v207 offset:36352
	ds_read_b128 v[184:187], v4 offset:6144
	ds_read_b128 v[4:7], v4 offset:6656
	s_waitcnt lgkmcnt(14)
	v_mfma_f32_32x32x16_bf16 v[20:35], v[156:159], v[92:95], v[20:35]
	v_exp_f32_e32 v122, v122
	v_exp_f32_e32 v123, v123
	ds_read_b64_tr_b16 v[92:93], v207 offset:39936
	ds_read_b64_tr_b16 v[94:95], v207 offset:40448
	s_waitcnt lgkmcnt(12)
	v_mfma_f32_32x32x16_bf16 v[36:51], v[152:155], v[14:17], v[36:51]
	v_exp_f32_e32 v124, v124
	v_exp_f32_e32 v125, v125
	ds_read_b128 v[14:17], v219
	s_waitcnt lgkmcnt(9)
	v_mfma_f32_32x32x16_bf16 v[20:35], v[152:155], v[88:91], v[20:35]
	v_exp_f32_e32 v126, v126
	v_exp_f32_e32 v127, v127
	s_add_u32 s98, s6, s34
	s_addc_u32 s99, s7, s35
	v_lshl_add_u64 v[254:255], v[8:9], 0, s[98:99]
	s_lshl_b32 s100, s60, 14
	s_add_i32 s100, s100, s58
	s_addk_i32 s100, 0x2000
	s_mov_b32 m0, s100
	s_nop 0
	global_load_lds_dwordx4 v[254:255], off
	s_waitcnt lgkmcnt(5)
	v_mfma_f32_32x32x16_bf16 v[36:51], v[148:151], v[84:87], v[36:51]
	v_exp_f32_e32 v128, v128
	v_exp_f32_e32 v129, v129
	s_waitcnt lgkmcnt(1)
	v_mfma_f32_32x32x16_bf16 v[20:35], v[148:151], v[92:95], v[20:35]
	v_exp_f32_e32 v130, v130
	v_exp_f32_e32 v131, v131
	s_waitcnt vmcnt(3) lgkmcnt(0)
	s_barrier
	s_add_i32 s16, s60, 1
	s_cmp_lg_u32 s60, 2
	s_cselect_b32 s59, s16, 0
	ds_read_b128 v[188:191], v219 offset:1024
	v_lshl_add_u32 v207, s10, 14, v214
	s_waitcnt lgkmcnt(1)
	v_mfma_f32_32x32x16_bf16 v[100:115], v[96:99], v[14:17], 0
	v_add_f32_e32 v84, v132, v133
	v_add_f32_e32 v84, v134, v84
	v_add_f32_e32 v84, v135, v84
	v_add_f32_e32 v84, v136, v84
	v_add_f32_e32 v84, v137, v84
	v_cvt_pk_bf16_f32 v160, v132, v133
	v_cvt_pk_bf16_f32 v161, v134, v135
	s_nop 0
	v_add_f32_e32 v84, v138, v84
	v_add_f32_e32 v84, v139, v84
	v_add_f32_e32 v84, v140, v84
	v_add_f32_e32 v148, v141, v84
	v_mfma_f32_32x32x16_bf16 v[84:99], v[164:167], v[14:17], 0
	v_cvt_pk_bf16_f32 v162, v136, v137
	v_cvt_pk_bf16_f32 v163, v138, v139
	ds_read_b128 v[14:17], v219 offset:2048
	ds_read_b64_tr_b16 v[132:133], v207 offset:24576
	ds_read_b64_tr_b16 v[134:135], v207 offset:25088
	s_waitcnt lgkmcnt(3)
	v_mfma_f32_32x32x16_bf16 v[100:115], v[168:171], v[188:191], v[100:115]
	v_add_f32_e32 v136, v142, v148
	v_add_f32_e32 v136, v143, v136
	v_add_f32_e32 v136, v144, v136
	v_add_f32_e32 v136, v145, v136
	v_cvt_pk_bf16_f32 v156, v140, v141
	v_cvt_pk_bf16_f32 v157, v142, v143
	v_mfma_f32_32x32x16_bf16 v[84:99], v[172:175], v[188:191], v[84:99]
	v_add_f32_e32 v136, v146, v136
	v_add_f32_e32 v136, v147, v136
	v_add_f32_e32 v136, v116, v136
	v_add_f32_e32 v148, v117, v136
	v_cvt_pk_bf16_f32 v158, v144, v145
	v_cvt_pk_bf16_f32 v159, v146, v147
	ds_read_b128 v[136:139], v219 offset:3072
	ds_read_b64_tr_b16 v[140:141], v207 offset:28672
	ds_read_b64_tr_b16 v[142:143], v207 offset:29184
	s_waitcnt lgkmcnt(5)
	v_mfma_f32_32x32x16_bf16 v[100:115], v[176:179], v[14:17], v[100:115]
	v_add_f32_e32 v144, v118, v148
	v_add_f32_e32 v144, v119, v144
	v_add_f32_e32 v144, v120, v144
	v_add_f32_e32 v144, v121, v144
	v_cvt_pk_bf16_f32 v152, v116, v117
	v_cvt_pk_bf16_f32 v153, v118, v119
	v_mfma_f32_32x32x16_bf16 v[84:99], v[180:183], v[14:17], v[84:99]
	v_add_f32_e32 v14, v122, v144
	v_add_f32_e32 v14, v123, v14
	v_add_f32_e32 v14, v124, v14
	v_add_f32_e32 v116, v125, v14
	v_cvt_pk_bf16_f32 v154, v120, v121
	v_cvt_pk_bf16_f32 v155, v122, v123
	ds_read_b64_tr_b16 v[14:15], v207 offset:25600
	ds_read_b64_tr_b16 v[16:17], v207 offset:26112
	s_waitcnt lgkmcnt(4)
	v_mfma_f32_32x32x16_bf16 v[100:115], v[184:187], v[136:139], v[100:115]
	v_add_f32_e32 v116, v126, v116
	v_add_f32_e32 v116, v127, v116
	v_add_f32_e32 v116, v128, v116
	v_add_f32_e32 v116, v129, v116
	v_cvt_pk_bf16_f32 v148, v124, v125
	v_cvt_pk_bf16_f32 v149, v126, v127
	v_mfma_f32_32x32x16_bf16 v[84:99], v[4:7], v[136:139], v[84:99]
	v_add_f32_e32 v4, v130, v116
	v_add_f32_e32 v4, v131, v4
	v_cvt_pk_bf16_f32 v150, v128, v129
	v_cvt_pk_bf16_f32 v151, v130, v131
	v_add_f32_e32 v225, v2, v4
	ds_read_b64_tr_b16 v[4:5], v207 offset:29696
	ds_read_b64_tr_b16 v[6:7], v207 offset:30208
	v_mfma_f32_32x32x16_bf16 v[68:83], v[160:163], v[132:135], v[68:83]
	v_exp_f32_e32 v100, v100
	v_exp_f32_e32 v101, v101
	ds_read_b64_tr_b16 v[10:11], v207 offset:26624
	ds_read_b64_tr_b16 v[12:13], v207 offset:27136
	s_waitcnt lgkmcnt(6)
; #define TWAIT_BAR(N) asm volatile("s_waitcnt vmcnt(" #N ") lgkmcnt(0)\n\ts_barrier" ::: "memory")
; #define RESC() do { if constexpr (!NOMAX) if (resc) { asm volatile("s_waitcnt lgkmcnt(0)" ::: "memory"); \
;         _Pragma("unroll") for (int d_ = 0; d_ < 2; ++d_) _Pragma("unroll") for (int r = 0; r < 16; ++r) o[d_][r] *= wsf[crow(r, hi)]; } } while (0)
; #define ROT() do { sl_prev = sl_cur; sl_cur = sl_next; sl_next = (sl_next == 2 * SLOTB) ? 0 : sl_next + SLOTB; } while (0)
; #define RESC() do { if constexpr (!NOMAX) if (resc) { asm volatile("s_waitcnt lgkmcnt(0)" ::: "memory"); \
;         _Pragma("unroll") for (int d_ = 0; d_ < 4; ++d_) _Pragma("unroll") for (int r = 0; r < 16; ++r) o[d_][r] *= wsf[crow(r, hi)]; } } while (0)
; #define ROT() do { sl_prev = sl_cur; sl_cur = sl_next; sl_next = (sl_next == 2) ? 0 : sl_next + 1; } while (0)
; #define RESC() do { if (resc) { asm volatile("s_waitcnt lgkmcnt(0)" ::: "memory"); \
;         _Pragma("unroll") for (int d_ = 0; d_ < 4; ++d_) _Pragma("unroll") for (int r = 0; r < 16; ++r) o[d_][r] *= wsf[crow(r, hi)]; } } while (0)
; template <bool NOMAX>
; __device__ __forceinline__ void diff_unit(const AttnCtx& C, int u, LAS unsigned char* lds) {
;     ...
;     int kk = 1;
;     for (; kk + 7 < n; kk += 2) {
;         STEP(pB0, pB1, pA0, pA1, kk, true, true, true, false);     TWAIT_BAR(3); RESC(); ROT();
;         STEP(pA0, pA1, pB0, pB1, kk + 1, true, true, true, false); TWAIT_BAR(3); RESC(); ROT();
	v_mfma_f32_32x32x16_bf16 v[52:67], v[160:163], v[140:143], v[52:67]
	v_exp_f32_e32 v102, v102
	v_exp_f32_e32 v103, v103
	s_add_u32 s98, s6, s36
	s_addc_u32 s99, s7, s37
	v_lshl_add_u64 v[254:255], v[204:205], 0, s[98:99]
	s_lshl_b32 s100, s60, 13
	s_add_i32 s100, s100, s49
	s_mov_b32 m0, s100
	s_nop 0
	global_load_lds_dwordx4 v[254:255], off
	ds_read_b64_tr_b16 v[116:117], v207 offset:30720
	ds_read_b64_tr_b16 v[118:119], v207 offset:31232
	s_waitcnt lgkmcnt(6)
	v_mfma_f32_32x32x16_bf16 v[68:83], v[156:159], v[14:17], v[68:83]
	v_exp_f32_e32 v104, v104
	v_exp_f32_e32 v105, v105
	ds_read_b64_tr_b16 v[14:15], v207 offset:27648
	ds_read_b64_tr_b16 v[16:17], v207 offset:28160
	s_waitcnt lgkmcnt(6)
	v_mfma_f32_32x32x16_bf16 v[52:67], v[156:159], v[4:7], v[52:67]
	v_exp_f32_e32 v106, v106
	v_exp_f32_e32 v107, v107
	ds_read_b64_tr_b16 v[4:5], v207 offset:31744
	ds_read_b64_tr_b16 v[6:7], v207 offset:32256
	s_waitcnt lgkmcnt(6)
	v_mfma_f32_32x32x16_bf16 v[68:83], v[152:155], v[10:13], v[68:83]
	v_exp_f32_e32 v108, v108
	v_exp_f32_e32 v109, v109
	s_add_u32 s98, s6, s38
	s_addc_u32 s99, s7, s39
	v_lshl_add_u64 v[254:255], v[8:9], 0, s[98:99]
	s_lshl_b32 s100, s59, 14
	s_add_i32 s100, s100, s58
	s_mov_b32 m0, s100
	s_nop 0
	global_load_lds_dwordx4 v[254:255], off
	ds_read_b64_tr_b16 v[10:11], v207 offset:32768
	ds_read_b64_tr_b16 v[12:13], v207 offset:33280
	s_waitcnt lgkmcnt(6)
	v_mfma_f32_32x32x16_bf16 v[52:67], v[152:155], v[116:119], v[52:67]
	v_exp_f32_e32 v110, v110
	v_exp_f32_e32 v111, v111
	ds_read_b64_tr_b16 v[116:117], v207 offset:36864
	ds_read_b64_tr_b16 v[118:119], v207 offset:37376
	s_waitcnt lgkmcnt(6)
	v_mfma_f32_32x32x16_bf16 v[68:83], v[148:151], v[14:17], v[68:83]
	v_exp_f32_e32 v112, v112
	v_exp_f32_e32 v113, v113
	ds_read_b64_tr_b16 v[14:15], v207 offset:33792
	ds_read_b64_tr_b16 v[16:17], v207 offset:34304
	s_waitcnt lgkmcnt(6)
	v_mfma_f32_32x32x16_bf16 v[52:67], v[148:151], v[4:7], v[52:67]
	v_exp_f32_e32 v114, v114
	v_exp_f32_e32 v115, v115
	ds_read_b64_tr_b16 v[4:5], v207 offset:37888
	ds_read_b64_tr_b16 v[6:7], v207 offset:38400
	v_lshl_add_u32 v2, s59, 13, v222
	ds_read_b128 v[192:195], v2
	ds_read_b128 v[184:187], v2 offset:512
	s_waitcnt lgkmcnt(8)
	v_mfma_f32_32x32x16_bf16 v[36:51], v[160:163], v[10:13], v[36:51]
	v_exp_f32_e32 v84, v84
	v_exp_f32_e32 v85, v85
	ds_read_b64_tr_b16 v[10:11], v207 offset:34816
	ds_read_b64_tr_b16 v[12:13], v207 offset:35328
	ds_read_b128 v[188:191], v2 offset:2048
	ds_read_b128 v[180:183], v2 offset:2560
	s_waitcnt lgkmcnt(10)
	v_mfma_f32_32x32x16_bf16 v[20:35], v[160:163], v[116:119], v[20:35]
	v_exp_f32_e32 v86, v86
	v_exp_f32_e32 v87, v87
	ds_read_b64_tr_b16 v[120:121], v207 offset:38912
	ds_read_b64_tr_b16 v[122:123], v207 offset:39424
	ds_read_b128 v[176:179], v2 offset:4096
	ds_read_b128 v[172:175], v2 offset:4608
	s_waitcnt lgkmcnt(12)
	v_mfma_f32_32x32x16_bf16 v[36:51], v[156:159], v[14:17], v[36:51]
	v_exp_f32_e32 v88, v88
	v_exp_f32_e32 v89, v89
	ds_read_b64_tr_b16 v[14:15], v207 offset:35840
	ds_read_b64_tr_b16 v[16:17], v207 offset:36352
	ds_read_b128 v[168:171], v2 offset:6144
	ds_read_b128 v[164:167], v2 offset:6656
	s_waitcnt lgkmcnt(14)
	v_mfma_f32_32x32x16_bf16 v[20:35], v[156:159], v[4:7], v[20:35]
	v_exp_f32_e32 v90, v90
	v_exp_f32_e32 v91, v91
	ds_read_b64_tr_b16 v[4:5], v207 offset:39936
	ds_read_b64_tr_b16 v[6:7], v207 offset:40448
	s_waitcnt lgkmcnt(12)
	v_mfma_f32_32x32x16_bf16 v[36:51], v[152:155], v[10:13], v[36:51]
	v_exp_f32_e32 v92, v92
	v_exp_f32_e32 v93, v93
	ds_read_b128 v[116:119], v219
	s_waitcnt lgkmcnt(9)
	v_mfma_f32_32x32x16_bf16 v[20:35], v[152:155], v[120:123], v[20:35]
	v_exp_f32_e32 v94, v94
	v_exp_f32_e32 v95, v95
	s_add_u32 s98, s6, s40
	s_addc_u32 s99, s7, s41
	v_lshl_add_u64 v[254:255], v[8:9], 0, s[98:99]
	s_lshl_b32 s100, s59, 14
	s_add_i32 s100, s100, s58
	s_addk_i32 s100, 0x2000
	s_mov_b32 m0, s100
	s_nop 0
	global_load_lds_dwordx4 v[254:255], off
	s_waitcnt lgkmcnt(5)
	v_mfma_f32_32x32x16_bf16 v[36:51], v[148:151], v[14:17], v[36:51]
	v_exp_f32_e32 v96, v96
	v_exp_f32_e32 v97, v97
	s_waitcnt lgkmcnt(1)
	v_mfma_f32_32x32x16_bf16 v[20:35], v[148:151], v[4:7], v[20:35]
	v_exp_f32_e32 v98, v98
	v_exp_f32_e32 v99, v99
	s_add_i32 s10, s59, 1
	s_cmp_lg_u32 s59, 2
	s_waitcnt vmcnt(3) lgkmcnt(0)
	s_barrier
	s_cselect_b32 s60, s10, 0
	s_add_i32 s16, s9, 2
	s_add_u32 s6, s6, 0x20000
	v_cmp_ge_u32_e32 vcc, s16, v226
	s_addc_u32 s7, s7, 0
	s_mov_b32 s11, s8
	s_cbranch_vccz .LBB0_463
	s_add_i32 s16, s9, -5
	s_branch .LBB0_467
